# e10 + dilated attention: end-of-unit workgroup barrier removed (last tile always in buffer 1, next unit first tile goes to buffer 0)
# speedup vs baseline: 1.0008x; 1.0008x over previous
; template <int MODE> ...
;     ...
;         __syncthreads();
; __global__ void __launch_bounds__(NT_, 2) fwd_mega(Args args) {
;     ...
;                     for (int u = bid; u < 4096; u += G) { const int bh = u & 255, r = u >> 8; const int c = r % dil, jb = r / dil;
;                         attn_unit<1>(lds, QKb, VTb, biasT, bh >> 3, bh & 7, c, dil, jb, AOb, LSEb, gi, 0.f, nullptr, 0.f, (bh & 7) != last_hp); last_hp = bh & 7; }
.LBB0_426:
	s_or_b64 exec, exec, s[0:1]
	s_add_i32 s26, s26, s74
	s_cmpk_gt_i32 s26, 0xfff
	s_waitcnt lgkmcnt(0)
	s_cbranch_scc1 .LBB0_466
